# scan type-1: o tile produced transposed by swapping MFMA operands and stored directly (permlane32 swap + dwordx4) without the LDS image; loader interleaves stage writes with next loads
# speedup vs baseline: 1.0143x; 1.0096x over previous
.LBB0_497:
	s_andn2_b64 vcc, exec, s[0:1]
	s_cbranch_vccnz .LBB0_520
	s_and_b32 s3, s2, 1
	s_ashr_i32 s14, s2, 1
	s_bitcmp1_b32 s2, 0
	s_cselect_b64 s[0:1], -1, 0
	s_add_u32 s12, s54, 0x15c00000
	s_addc_u32 s13, s55, 0
	s_cmp_eq_u32 s3, 0
	s_cselect_b64 s[6:7], -1, 0
	s_mov_b32 s3, 0x380000
	s_and_b64 s[8:9], s[6:7], exec
	s_cselect_b32 s3, s3, 0x480000
	s_cselect_b32 s9, s52, s12
	s_mul_hi_i32 s12, s3, s14
	s_mul_i32 s3, s3, s14
	s_cselect_b32 s8, s53, s13
	s_add_u32 s16, s9, s3
	v_mbcnt_lo_u32_b32 v0, -1, 0
	s_addc_u32 s17, s8, s12
	v_mbcnt_hi_u32_b32 v190, -1, v0
	v_cndmask_b32_e64 v0, 0, 1, s[0:1]
	s_cmpk_lt_u32 s85, 0x100
	s_mov_b64 s[8:9], -1
	v_cmp_ne_u32_e64 s[0:1], 1, v0
	s_cbranch_scc0 .LBB0_507
	s_ashr_i32 s3, s2, 3
	s_and_b32 s13, s14, 3
	s_setprio 3
	s_and_b64 vcc, exec, s[0:1]
	s_mul_i32 s12, s95, 0x1400
	s_cbranch_vccnz .LBB0_503
	s_lshl_b32 s8, s14, 6
	s_ashr_i32 s9, s8, 31
	s_lshl_b64 s[8:9], s[8:9], 2
	v_mov_b32_e32 v20, v190
	s_add_u32 s8, s54, s8
	s_addc_u32 s9, s55, s9
	v_ashrrev_i32_e32 v22, 5, v20
	s_lshl_b32 s14, s95, 12
	v_ashrrev_i32_e32 v21, 31, v20
	v_lshlrev_b32_e32 v16, 7, v22
	s_add_u32 s14, s16, s14
	v_lshl_add_u64 v[0:1], v[20:21], 2, s[8:9]
	v_and_b32_e32 v21, 31, v20
	v_ashrrev_i32_e32 v17, 31, v16
	s_addc_u32 s15, s17, 0
	v_add_co_u32_e32 v0, vcc, 0x1a40000, v0
	v_mov_b32_e32 v165, 0
	v_lshlrev_b32_e32 v164, 3, v21
	v_lshl_add_u64 v[16:17], v[16:17], 1, s[14:15]
	v_addc_co_u32_e32 v1, vcc, 0, v1, vcc
	v_lshl_add_u64 v[172:173], v[16:17], 0, v[164:165]
	global_load_dword v19, v[0:1], off
	global_load_dwordx2 v[188:189], v[172:173], off
	global_load_dwordx2 v[182:183], v[172:173], off offset:512
	global_load_dwordx2 v[178:179], v[172:173], off offset:1024
	global_load_dwordx2 v[174:175], v[172:173], off offset:1536
	global_load_dwordx2 v[186:187], v[172:173], off offset:2048
	global_load_dwordx2 v[184:185], v[172:173], off offset:2560
	global_load_dwordx2 v[180:181], v[172:173], off offset:3072
	global_load_dwordx2 v[176:177], v[172:173], off offset:3584
	s_movk_i32 s8, 0x140
	v_bfe_u32 v23, v20, 2, 3
	s_movk_i32 s26, 0x50
	v_lshlrev_b32_e32 v20, 4, v20
	v_lshlrev_b32_e32 v193, 4, v22
	v_mul_lo_u32 v24, v22, s8
	v_lshl_or_b32 v22, v22, 3, v23
	s_lshl_b32 s8, s13, 8
	s_add_i32 s14, s12, 0
	s_lshl_b32 s15, s3, 23
	v_mul_u32_u24_e32 v192, 0x110, v21
	v_mul_u32_u24_e32 v194, 0x90, v21
	v_lshlrev_b32_e32 v21, 1, v21
	v_and_b32_e32 v20, 48, v20
	v_mul_lo_u32 v23, v22, s26
	s_and_b32 s26, s85, 0xc0
	s_add_i32 s14, s14, 0x1e800
	s_or_b32 s8, s15, s8
	s_waitcnt lgkmcnt(0)
	s_barrier
	v_add3_u32 v195, s14, v24, v21
	v_lshl_or_b32 v164, v22, 11, v20
	v_add_u32_e32 v21, s14, v23
	s_or_b32 s8, s8, s26
	s_mov_b32 s9, 0
	v_mov_b32_e32 v191, 0x12000
	v_mov_b32_e32 v167, v165
	v_mov_b32_e32 v169, v165
	v_mov_b32_e32 v171, v165
	v_mov_b32_e32 v0, v165
	v_mov_b32_e32 v1, v165
	v_mov_b32_e32 v2, v165
	v_mov_b32_e32 v3, v165
	v_mov_b32_e32 v4, v165
	v_mov_b32_e32 v5, v165
	v_mov_b32_e32 v6, v165
	v_mov_b32_e32 v7, v165
	v_mov_b32_e32 v8, v165
	v_mov_b32_e32 v9, v165
	v_mov_b32_e32 v10, v165
	v_mov_b32_e32 v11, v165
	v_mov_b32_e32 v12, v165
	v_mov_b32_e32 v13, v165
	v_mov_b32_e32 v14, v165
	v_mov_b32_e32 v15, v165
	v_mov_b32_e32 v16, v165
	v_mov_b32_e32 v17, v165
	v_mov_b32_e32 v18, v165
	v_add_u32_e32 v166, 0x8000, v164
	v_add_u32_e32 v168, 0x10000, v164
	v_add_u32_e32 v170, 0x18000, v164
	s_bitset1_b32 s8, 10
	v_add_u32_e32 v196, v21, v20
	v_mov_b32_e32 v20, v165
	v_mov_b32_e32 v21, v165
	v_mov_b32_e32 v22, v165
	v_mov_b32_e32 v23, v165
	v_mov_b32_e32 v24, v165
	v_mov_b32_e32 v25, v165
	v_mov_b32_e32 v26, v165
	v_mov_b32_e32 v27, v165
	v_mov_b32_e32 v28, v165
	v_mov_b32_e32 v29, v165
	v_mov_b32_e32 v30, v165
	v_mov_b32_e32 v31, v165
	v_mov_b32_e32 v32, v165
	v_mov_b32_e32 v33, v165
	v_mov_b32_e32 v34, v165
	v_mov_b32_e32 v35, v165
	v_mov_b32_e32 v36, v165
	v_mov_b32_e32 v37, v165
	v_mov_b32_e32 v38, v165
	v_mov_b32_e32 v39, v165
	v_mov_b32_e32 v40, v165
	v_mov_b32_e32 v41, v165
	v_mov_b32_e32 v42, v165
	v_mov_b32_e32 v43, v165
	s_waitcnt vmcnt(0)
	v_mul_f32_e32 v19, 0x3fb8aa3b, v19
	v_exp_f32_e32 v197, v19
	v_mov_b32_e32 v19, v165
	v_mov_b32_e32 v44, v165
	v_mov_b32_e32 v45, v165
	v_mov_b32_e32 v46, v165
	v_mov_b32_e32 v47, v165
	v_mov_b32_e32 v48, v165
	v_mov_b32_e32 v49, v165
	v_mov_b32_e32 v50, v165
	v_mov_b32_e32 v51, v165
	v_mov_b32_e32 v52, v165
	v_mov_b32_e32 v53, v165
	v_mov_b32_e32 v54, v165
	v_mov_b32_e32 v55, v165
	v_mov_b32_e32 v56, v165
	v_mov_b32_e32 v57, v165
	v_mov_b32_e32 v58, v165
	v_mov_b32_e32 v59, v165
	v_mov_b32_e32 v60, v165
	v_mov_b32_e32 v61, v165
	v_mov_b32_e32 v62, v165
	v_mov_b32_e32 v63, v165
	v_mbcnt_lo_u32_b32 v164, -1, 0
	v_mbcnt_hi_u32_b32 v164, -1, v164
	v_lshrrev_b32_e32 v166, 5, v164
	v_and_b32_e32 v164, 31, v164
	v_lshlrev_b32_e32 v166, 4, v166
	v_lshl_or_b32 v164, v164, 11, v166
	v_add_u32_e32 v166, 0x10000, v164
.LBB0_501:
	s_bitcmp1_b32 s9, 0
	s_cselect_b32 s14, 0xf400, 0
	s_add_i32 s14, s14, 0
	v_add3_u32 v152, s14, v192, v193
	ds_read_b128 v[64:67], v152
	ds_read_b128 v[88:91], v152 offset:32
	ds_read_b128 v[68:71], v152 offset:8704
	ds_read_b128 v[92:95], v152 offset:8736
	ds_read_b128 v[72:75], v152 offset:17408
	ds_read_b128 v[128:131], v152 offset:17440
	ds_read_b128 v[80:83], v152 offset:26112
	ds_read_b128 v[136:139], v152 offset:26144
	v_add3_u32 v198, s14, v194, v193
	v_cvt_pk_bf16_f32 v84, v0, v1
	v_cvt_pk_bf16_f32 v85, v2, v3
	v_cvt_pk_bf16_f32 v86, v4, v5
	v_cvt_pk_bf16_f32 v87, v6, v7
	s_waitcnt lgkmcnt(7)
	s_nop 0
	v_mfma_f32_32x32x16_bf16 v[112:127], v[64:67], v[84:87], 0
	s_waitcnt lgkmcnt(5)
	v_mfma_f32_32x32x16_bf16 v[96:111], v[68:71], v[84:87], 0
	s_waitcnt lgkmcnt(3)
	v_mfma_f32_32x32x16_bf16 v[64:79], v[84:87], v[72:75], 0
	ds_read_b128 v[132:135], v152 offset:64
	ds_read_b128 v[140:143], v152 offset:8768
	ds_read_b128 v[148:151], v152 offset:17472
	ds_read_b128 v[144:147], v152 offset:26176
	v_cvt_pk_bf16_f32 v160, v8, v9
	v_cvt_pk_bf16_f32 v161, v10, v11
	v_cvt_pk_bf16_f32 v162, v12, v13
	v_cvt_pk_bf16_f32 v163, v14, v15
	s_nop 1
	v_mfma_f32_32x32x16_bf16 v[112:127], v[88:91], v[160:163], v[112:127]
	v_mfma_f32_32x32x16_bf16 v[96:111], v[92:95], v[160:163], v[96:111]
	s_waitcnt lgkmcnt(6)
	v_mfma_f32_32x32x16_bf16 v[64:79], v[160:163], v[128:131], v[64:79]
	ds_read_b128 v[88:91], v152 offset:96
	ds_read_b128 v[92:95], v152 offset:8800
	ds_read_b128 v[128:131], v152 offset:17504
	ds_read_b128 v[156:159], v152 offset:26208
	v_cvt_pk_bf16_f32 v200, v16, v17
	v_cvt_pk_bf16_f32 v201, v18, v19
	v_cvt_pk_bf16_f32 v202, v20, v21
	v_cvt_pk_bf16_f32 v203, v22, v23
	s_waitcnt lgkmcnt(7)
	s_nop 0
	v_mfma_f32_32x32x16_bf16 v[112:127], v[132:135], v[200:203], v[112:127]
	s_waitcnt lgkmcnt(6)
	v_mfma_f32_32x32x16_bf16 v[96:111], v[140:143], v[200:203], v[96:111]
	s_waitcnt lgkmcnt(5)
	v_mfma_f32_32x32x16_bf16 v[64:79], v[200:203], v[148:151], v[64:79]
	ds_read_b128 v[132:135], v152 offset:128
	ds_read_b128 v[140:143], v152 offset:8832
	ds_read_b128 v[148:151], v152 offset:17536
	ds_read_b128 v[204:207], v152 offset:26240
	v_cvt_pk_bf16_f32 v208, v24, v25
	v_cvt_pk_bf16_f32 v209, v26, v27
	v_cvt_pk_bf16_f32 v210, v28, v29
	v_cvt_pk_bf16_f32 v211, v30, v31
	s_waitcnt lgkmcnt(7)
	s_nop 0
	v_mfma_f32_32x32x16_bf16 v[112:127], v[88:91], v[208:211], v[112:127]
	s_waitcnt lgkmcnt(6)
	v_mfma_f32_32x32x16_bf16 v[96:111], v[92:95], v[208:211], v[96:111]
	s_waitcnt lgkmcnt(5)
	v_mfma_f32_32x32x16_bf16 v[64:79], v[208:211], v[128:131], v[64:79]
	ds_read_b128 v[88:91], v152 offset:160
	ds_read_b128 v[92:95], v152 offset:8864
	ds_read_b128 v[128:131], v152 offset:17568
	ds_read_b128 v[212:215], v152 offset:26272
	v_cvt_pk_bf16_f32 v216, v32, v33
	v_cvt_pk_bf16_f32 v217, v34, v35
	v_cvt_pk_bf16_f32 v218, v36, v37
	v_cvt_pk_bf16_f32 v219, v38, v39
	s_waitcnt lgkmcnt(7)
	s_nop 0
	v_mfma_f32_32x32x16_bf16 v[112:127], v[132:135], v[216:219], v[112:127]
	s_waitcnt lgkmcnt(6)
	v_mfma_f32_32x32x16_bf16 v[96:111], v[140:143], v[216:219], v[96:111]
	s_waitcnt lgkmcnt(5)
	v_mfma_f32_32x32x16_bf16 v[64:79], v[216:219], v[148:151], v[64:79]
	ds_read_b128 v[132:135], v152 offset:192
	ds_read_b128 v[140:143], v152 offset:8896
	ds_read_b128 v[148:151], v152 offset:17600
	ds_read_b128 v[220:223], v152 offset:26304
	v_cvt_pk_bf16_f32 v224, v40, v41
	v_cvt_pk_bf16_f32 v225, v42, v43
	v_cvt_pk_bf16_f32 v226, v44, v45
	v_cvt_pk_bf16_f32 v227, v46, v47
	s_waitcnt lgkmcnt(7)
	s_nop 0
	v_mfma_f32_32x32x16_bf16 v[112:127], v[88:91], v[224:227], v[112:127]
	s_waitcnt lgkmcnt(6)
	v_mfma_f32_32x32x16_bf16 v[96:111], v[92:95], v[224:227], v[96:111]
	s_waitcnt lgkmcnt(5)
	v_mfma_f32_32x32x16_bf16 v[64:79], v[224:227], v[128:131], v[64:79]
	ds_read_b128 v[88:91], v152 offset:224
	ds_read_b128 v[92:95], v152 offset:8928
	ds_read_b128 v[228:231], v152 offset:17632
	ds_read_b128 v[152:155], v152 offset:26336
	v_cvt_pk_bf16_f32 v232, v48, v49
	v_cvt_pk_bf16_f32 v233, v50, v51
	v_cvt_pk_bf16_f32 v234, v52, v53
	v_cvt_pk_bf16_f32 v235, v54, v55
	s_waitcnt lgkmcnt(7)
	s_nop 0
	v_mfma_f32_32x32x16_bf16 v[112:127], v[132:135], v[232:235], v[112:127]
	s_waitcnt lgkmcnt(6)
	v_mfma_f32_32x32x16_bf16 v[96:111], v[140:143], v[232:235], v[96:111]
	s_waitcnt lgkmcnt(5)
	v_mfma_f32_32x32x16_bf16 v[64:79], v[232:235], v[148:151], v[64:79]
	ds_read_b128 v[148:151], v198 offset:53248
	ds_read_b128 v[132:135], v198 offset:53280
	ds_read_b128 v[140:143], v198 offset:57856
	ds_read_b128 v[128:131], v198 offset:57888
	v_cvt_pk_bf16_f32 v236, v56, v57
	v_cvt_pk_bf16_f32 v237, v58, v59
	v_cvt_pk_bf16_f32 v238, v60, v61
	v_cvt_pk_bf16_f32 v239, v62, v63
	s_waitcnt lgkmcnt(7)
	s_nop 0
	v_mfma_f32_32x32x16_bf16 v[112:127], v[88:91], v[236:239], v[112:127]
	s_waitcnt lgkmcnt(6)
	v_mfma_f32_32x32x16_bf16 v[96:111], v[92:95], v[236:239], v[96:111]
	s_waitcnt lgkmcnt(5)
	v_mfma_f32_32x32x16_bf16 v[64:79], v[236:239], v[228:231], v[64:79]
	s_waitcnt vmcnt(11)
	v_lshlrev_b32_e32 v88, 16, v188
	v_and_b32_e32 v89, 0xffff0000, v188
	s_nop 4
	v_add_f32_e64 v112, v88, -v112
	v_add_f32_e64 v113, v89, -v113
	v_lshlrev_b32_e32 v88, 16, v189
	v_and_b32_e32 v89, 0xffff0000, v189
	v_pk_add_f32 v[114:115], v[88:89], v[114:115] neg_lo:[0,1] neg_hi:[0,1]
	v_mfma_f32_32x32x16_bf16 v[80:95], v[84:87], v[80:83], 0
	s_waitcnt vmcnt(7)
	v_lshlrev_b32_e32 v188, 16, v186
	v_and_b32_e32 v189, 0xffff0000, v186
	v_lshlrev_b32_e32 v186, 16, v187
	v_and_b32_e32 v187, 0xffff0000, v187
	v_pk_add_f32 v[98:99], v[186:187], v[98:99] neg_lo:[0,1] neg_hi:[0,1]
	v_lshlrev_b32_e32 v186, 16, v182
	v_and_b32_e32 v187, 0xffff0000, v182
	v_mfma_f32_32x32x16_bf16 v[80:95], v[160:163], v[136:139], v[80:95]
	v_lshlrev_b32_e32 v136, 16, v183
	v_and_b32_e32 v137, 0xffff0000, v183
	v_add_f32_e64 v118, v136, -v118
	v_add_f32_e64 v119, v137, -v119
	s_waitcnt vmcnt(6)
	v_lshlrev_b32_e32 v136, 16, v184
	v_and_b32_e32 v137, 0xffff0000, v184
	v_pk_add_f32 v[136:137], v[136:137], v[100:101] neg_lo:[0,1] neg_hi:[0,1]
	v_lshlrev_b32_e32 v100, 16, v185
	v_mfma_f32_32x32x16_bf16 v[80:95], v[200:203], v[144:147], v[80:95]
	v_and_b32_e32 v101, 0xffff0000, v185
	v_add_f32_e64 v138, v100, -v102
	v_add_f32_e64 v139, v101, -v103
	v_lshlrev_b32_e32 v100, 16, v178
	v_and_b32_e32 v101, 0xffff0000, v178
	v_pk_add_f32 v[100:101], v[100:101], v[120:121] neg_lo:[0,1] neg_hi:[0,1]
	s_waitcnt vmcnt(5)
	v_lshlrev_b32_e32 v120, 16, v180
	v_and_b32_e32 v121, 0xffff0000, v180
	v_mfma_f32_32x32x16_bf16 v[80:95], v[208:211], v[156:159], v[80:95]
	v_lshlrev_b32_e32 v102, 16, v179
	v_and_b32_e32 v103, 0xffff0000, v179
	v_add_f32_e64 v120, v120, -v104
	v_add_f32_e64 v121, v121, -v105
	v_lshlrev_b32_e32 v104, 16, v181
	v_and_b32_e32 v105, 0xffff0000, v181
	v_pk_add_f32 v[102:103], v[102:103], v[122:123] neg_lo:[0,1] neg_hi:[0,1]
	v_pk_add_f32 v[122:123], v[104:105], v[106:107] neg_lo:[0,1] neg_hi:[0,1]
	v_mfma_f32_32x32x16_bf16 v[80:95], v[216:219], v[204:207], v[80:95]
	v_lshlrev_b32_e32 v104, 16, v174
	v_and_b32_e32 v105, 0xffff0000, v174
	v_add_f32_e64 v106, v104, -v124
	v_add_f32_e64 v107, v105, -v125
	v_lshlrev_b32_e32 v104, 16, v175
	v_and_b32_e32 v105, 0xffff0000, v175
	v_pk_add_f32 v[124:125], v[104:105], v[126:127] neg_lo:[0,1] neg_hi:[0,1]
	s_waitcnt vmcnt(4)
	v_lshlrev_b32_e32 v104, 16, v176
	v_mfma_f32_32x32x16_bf16 v[80:95], v[224:227], v[212:215], v[80:95]
	v_and_b32_e32 v105, 0xffff0000, v176
	v_add_f32_e64 v126, v104, -v108
	v_add_f32_e64 v127, v105, -v109
	v_lshlrev_b32_e32 v104, 16, v177
	v_and_b32_e32 v105, 0xffff0000, v177
	v_pk_add_f32 v[96:97], v[188:189], v[96:97] neg_lo:[0,1] neg_hi:[0,1]
	v_pk_add_f32 v[116:117], v[186:187], v[116:117] neg_lo:[0,1] neg_hi:[0,1]
	v_pk_add_f32 v[144:145], v[104:105], v[110:111] neg_lo:[0,1] neg_hi:[0,1]
	v_mfma_f32_32x32x16_bf16 v[80:95], v[232:235], v[220:223], v[80:95]
	v_cvt_pk_bf16_f32 v108, v112, v113
	v_cvt_pk_bf16_f32 v109, v114, v115
	v_cvt_pk_bf16_f32 v110, v116, v117
	v_cvt_pk_bf16_f32 v111, v118, v119
	v_cvt_pk_bf16_f32 v104, v100, v101
	v_cvt_pk_bf16_f32 v105, v102, v103
	v_cvt_pk_bf16_f32 v106, v106, v107
	v_cvt_pk_bf16_f32 v107, v124, v125
	v_cvt_pk_bf16_f32 v100, v96, v97
	v_cvt_pk_bf16_f32 v101, v98, v99
	v_cvt_pk_bf16_f32 v102, v136, v137
	v_cvt_pk_bf16_f32 v103, v138, v139
	v_cvt_pk_bf16_f32 v96, v120, v121
	v_cvt_pk_bf16_f32 v97, v122, v123
	v_cvt_pk_bf16_f32 v98, v126, v127
	v_cvt_pk_bf16_f32 v99, v144, v145
	s_add_i32 s14, s9, 1
	s_cmp_lg_u32 s9, 63
	s_cselect_b32 s15, s14, 63
	v_mad_u64_u32 v[112:113], s[26:27], s15, v191, v[172:173]
	global_load_dwordx2 v[188:189], v[112:113], off
	global_load_dwordx2 v[182:183], v[112:113], off offset:512
	global_load_dwordx2 v[178:179], v[112:113], off offset:1024
	global_load_dwordx2 v[174:175], v[112:113], off offset:1536
	global_load_dwordx2 v[186:187], v[112:113], off offset:2048
	global_load_dwordx2 v[184:185], v[112:113], off offset:2560
	global_load_dwordx2 v[180:181], v[112:113], off offset:3072
	global_load_dwordx2 v[176:177], v[112:113], off offset:3584
	ds_read_b128 v[112:115], v198 offset:53312
	ds_read_b128 v[116:119], v198 offset:53344
	ds_read_b128 v[120:123], v198 offset:57920
	ds_read_b128 v[124:127], v198 offset:57952
	v_readlane_b32 s9, v197, s9
	s_waitcnt lgkmcnt(8)
	v_mfma_f32_32x32x16_bf16 v[80:95], v[236:239], v[152:155], v[80:95]
	s_waitcnt lgkmcnt(7)
	v_mfma_f32_32x32x16_bf16 v[64:79], v[108:111], v[148:151], v[64:79]
	v_mov_b32_e32 v144, s9
	v_mul_f32_e32 v0, v0, v144
	v_mul_f32_e32 v1, v1, v144
	v_mul_f32_e32 v2, v2, v144
	v_mul_f32_e32 v3, v3, v144
	v_mul_f32_e32 v4, v4, v144
	v_mul_f32_e32 v5, v5, v144
	s_waitcnt lgkmcnt(5)
	v_mfma_f32_32x32x16_bf16 v[80:95], v[108:111], v[140:143], v[80:95]
	v_mul_f32_e32 v6, v6, v144
	v_mul_f32_e32 v7, v7, v144
	v_mul_f32_e32 v8, v8, v144
	v_mul_f32_e32 v9, v9, v144
	v_mul_f32_e32 v10, v10, v144
	v_mul_f32_e32 v11, v11, v144
	v_mul_f32_e32 v12, v12, v144
	v_mul_f32_e32 v13, v13, v144
	v_mul_f32_e32 v14, v14, v144
	v_mul_f32_e32 v15, v15, v144
	v_mul_f32_e32 v16, v16, v144
	v_mul_f32_e32 v17, v17, v144
	v_mul_f32_e32 v18, v18, v144
	v_mfma_f32_32x32x16_bf16 v[64:79], v[104:107], v[132:135], v[64:79]
	v_mul_f32_e32 v19, v19, v144
	v_mul_f32_e32 v20, v20, v144
	v_mul_f32_e32 v21, v21, v144
	v_mul_f32_e32 v22, v22, v144
	v_mul_f32_e32 v23, v23, v144
	v_mul_f32_e32 v24, v24, v144
	v_mul_f32_e32 v25, v25, v144
	s_waitcnt lgkmcnt(4)
	v_mfma_f32_32x32x16_bf16 v[80:95], v[104:107], v[128:131], v[80:95]
	v_mul_f32_e32 v26, v26, v144
	v_mul_f32_e32 v27, v27, v144
	v_mul_f32_e32 v28, v28, v144
	v_mul_f32_e32 v29, v29, v144
	v_mul_f32_e32 v30, v30, v144
	v_mul_f32_e32 v31, v31, v144
	ds_read_b128 v[128:131], v198 offset:34816
	ds_read_b128 v[132:135], v198 offset:39424
	ds_read_b128 v[136:139], v198 offset:44032
	ds_read_b128 v[140:143], v198 offset:48640
	s_waitcnt lgkmcnt(7)
	v_mfma_f32_32x32x16_bf16 v[64:79], v[100:103], v[112:115], v[64:79]
	v_mul_f32_e32 v32, v32, v144
	v_mul_f32_e32 v33, v33, v144
	v_mul_f32_e32 v34, v34, v144
	v_mul_f32_e32 v35, v35, v144
	v_mul_f32_e32 v36, v36, v144
	v_mul_f32_e32 v37, v37, v144
	v_mul_f32_e32 v38, v38, v144
	s_waitcnt lgkmcnt(5)
	v_mfma_f32_32x32x16_bf16 v[80:95], v[100:103], v[120:123], v[80:95]
	v_mul_f32_e32 v39, v39, v144
	v_mul_f32_e32 v40, v40, v144
	v_mul_f32_e32 v41, v41, v144
	v_mul_f32_e32 v42, v42, v144
	v_mul_f32_e32 v43, v43, v144
	v_mul_f32_e32 v44, v44, v144
	v_mul_f32_e32 v45, v45, v144
	v_mul_f32_e32 v46, v46, v144
	v_mul_f32_e32 v47, v47, v144
	v_mul_f32_e32 v48, v48, v144
	v_mul_f32_e32 v49, v49, v144
	v_mul_f32_e32 v50, v50, v144
	v_mul_f32_e32 v51, v51, v144
	v_mfma_f32_32x32x16_bf16 v[64:79], v[96:99], v[116:119], v[64:79]
	v_mul_f32_e32 v52, v52, v144
	v_mul_f32_e32 v53, v53, v144
	v_mul_f32_e32 v54, v54, v144
	v_mul_f32_e32 v55, v55, v144
	v_mul_f32_e32 v56, v56, v144
	v_mul_f32_e32 v57, v57, v144
	v_mul_f32_e32 v58, v58, v144
	s_waitcnt lgkmcnt(4)
	v_mfma_f32_32x32x16_bf16 v[80:95], v[96:99], v[124:127], v[80:95]
	v_mul_f32_e32 v59, v59, v144
	v_mul_f32_e32 v60, v60, v144
	v_mul_f32_e32 v61, v61, v144
	v_mul_f32_e32 v62, v62, v144
	v_mul_f32_e32 v63, v63, v144
	ds_read_b128 v[112:115], v198 offset:34848
	ds_read_b128 v[116:119], v198 offset:39456
	ds_read_b128 v[120:123], v198 offset:44064
	ds_read_b128 v[124:127], v198 offset:48672
	s_waitcnt lgkmcnt(7)
	v_mfma_f32_32x32x16_bf16 v[0:15], v[128:131], v[108:111], v[0:15]
	s_waitcnt lgkmcnt(5)
	v_mfma_f32_32x32x16_bf16 v[32:47], v[136:139], v[108:111], v[32:47]
	ds_read_b128 v[128:131], v198 offset:34880
	ds_read_b128 v[136:139], v198 offset:39488
	ds_read_b128 v[144:147], v198 offset:44096
	ds_read_b128 v[148:151], v198 offset:48704
	s_waitcnt lgkmcnt(7)
	v_mfma_f32_32x32x16_bf16 v[0:15], v[112:115], v[104:107], v[0:15]
	s_waitcnt lgkmcnt(5)
	v_mfma_f32_32x32x16_bf16 v[32:47], v[120:123], v[104:107], v[32:47]
	ds_read_b128 v[112:115], v198 offset:34912
	ds_read_b128 v[120:123], v198 offset:39520
	ds_read_b128 v[152:155], v198 offset:44128
	ds_read_b128 v[156:159], v198 offset:48736
	s_waitcnt lgkmcnt(7)
	v_mfma_f32_32x32x16_bf16 v[0:15], v[128:131], v[100:103], v[0:15]
	s_waitcnt lgkmcnt(5)
	v_mfma_f32_32x32x16_bf16 v[32:47], v[144:147], v[100:103], v[32:47]
	s_waitcnt lgkmcnt(3)
	v_mfma_f32_32x32x16_bf16 v[0:15], v[112:115], v[96:99], v[0:15]
	s_waitcnt lgkmcnt(1)
	v_mfma_f32_32x32x16_bf16 v[32:47], v[152:155], v[96:99], v[32:47]
	v_mfma_f32_32x32x16_bf16 v[16:31], v[132:135], v[108:111], v[16:31]
	v_cvt_pk_bf16_f32 v64, v64, v65
	v_cvt_pk_bf16_f32 v65, v66, v67
	v_cvt_pk_bf16_f32 v66, v68, v69
	v_cvt_pk_bf16_f32 v67, v70, v71
	v_cvt_pk_bf16_f32 v68, v72, v73
	v_cvt_pk_bf16_f32 v69, v74, v75
	v_cvt_pk_bf16_f32 v70, v76, v77
	v_mfma_f32_32x32x16_bf16 v[16:31], v[116:119], v[104:107], v[16:31]
	v_cvt_pk_bf16_f32 v71, v78, v79
	v_cvt_pk_bf16_f32 v72, v80, v81
	v_cvt_pk_bf16_f32 v73, v82, v83
	v_cvt_pk_bf16_f32 v74, v84, v85
	v_cvt_pk_bf16_f32 v75, v86, v87
	v_cvt_pk_bf16_f32 v76, v88, v89
	v_cvt_pk_bf16_f32 v77, v90, v91
	v_mfma_f32_32x32x16_bf16 v[16:31], v[136:139], v[100:103], v[16:31]
	v_cvt_pk_bf16_f32 v78, v92, v93
	v_cvt_pk_bf16_f32 v79, v94, v95
	v_mfma_f32_32x32x16_bf16 v[16:31], v[120:123], v[96:99], v[16:31]
	v_mfma_f32_32x32x16_bf16 v[48:63], v[140:143], v[108:111], v[48:63]
	s_nop 1
	v_permlane32_swap_b32_e32 v64, v66
	v_permlane32_swap_b32_e32 v65, v67
	v_permlane32_swap_b32_e32 v68, v70
	v_permlane32_swap_b32_e32 v69, v71
	v_permlane32_swap_b32_e32 v72, v74
	v_permlane32_swap_b32_e32 v73, v75
	v_permlane32_swap_b32_e32 v76, v78
	v_permlane32_swap_b32_e32 v77, v79
	s_ashr_i32 s9, s8, 31
	s_add_u32 s26, s80, s8
	s_addc_u32 s27, s81, s9
	v_mfma_f32_32x32x16_bf16 v[48:63], v[124:127], v[104:107], v[48:63]
	global_store_dwordx4 v164, v[64:67], s[26:27]
	global_store_dwordx4 v164, v[68:71], s[26:27] offset:32
	global_store_dwordx4 v166, v[72:75], s[26:27]
	global_store_dwordx4 v166, v[76:79], s[26:27] offset:32
	s_waitcnt lgkmcnt(0)
	s_waitcnt lgkmcnt(0)
	v_mfma_f32_32x32x16_bf16 v[48:63], v[148:151], v[100:103], v[48:63]
	s_barrier
	s_add_i32 s8, s8, 0x20000
	s_cmp_eq_u32 s14, 64
	s_mov_b32 s9, s14
	v_mfma_f32_32x32x16_bf16 v[48:63], v[156:159], v[96:99], v[48:63]
	s_cbranch_scc0 .LBB0_501
	s_mov_b64 s[8:9], 0

.Lpf_nopub_a1:
	s_add_i32 s0, s0, 3
	s_mul_i32 s0, s3, s0
	s_add_u32 s7, s16, s0
	s_addc_u32 s38, s17, 0
	s_add_u32 s0, s7, s6
	s_addc_u32 s1, s38, 0
	s_add_u32 s28, s7, s14
	s_addc_u32 s29, s38, 0
	s_add_u32 s34, s7, s15
	s_addc_u32 s35, s38, 0
	s_add_u32 s60, s7, s26
	s_addc_u32 s61, s38, 0
	ds_write_b128 v124, v[0:3] offset:62464
	v_lshl_add_u64 v[0:1], s[0:1], 0, v[112:113]
	global_load_dwordx4 v[0:3], v[0:1], off
	v_add_u32_e32 v145, v141, v123
	ds_write_b128 v145, v[4:7]
	v_lshl_add_u64 v[4:5], s[28:29], 0, v[112:113]
	global_load_dwordx4 v[4:7], v[4:5], off
	v_add_u32_e32 v145, v142, v125
	ds_write_b128 v145, v[8:11]
	v_lshl_add_u64 v[8:9], s[34:35], 0, v[112:113]
	global_load_dwordx4 v[8:11], v[8:9], off
	ds_write_b128 v128, v[12:15] offset:62464
	v_lshl_add_u64 v[12:13], s[0:1], 0, v[114:115]
	global_load_dwordx4 v[12:15], v[12:13], off
	v_add_u32_e32 v145, v141, v127
	ds_write_b128 v145, v[16:19]
	v_lshl_add_u64 v[16:17], s[28:29], 0, v[114:115]
	global_load_dwordx4 v[16:19], v[16:17], off
	v_add_u32_e32 v145, v142, v129
	ds_write_b128 v145, v[20:23]
	v_lshl_add_u64 v[20:21], s[34:35], 0, v[114:115]
	global_load_dwordx4 v[20:23], v[20:21], off
	ds_write_b128 v132, v[24:27] offset:62464
	v_lshl_add_u64 v[24:25], s[0:1], 0, v[116:117]
	global_load_dwordx4 v[24:27], v[24:25], off
	v_add_u32_e32 v145, v141, v131
	ds_write_b128 v145, v[28:31]
	v_lshl_add_u64 v[28:29], s[28:29], 0, v[116:117]
	global_load_dwordx4 v[28:31], v[28:29], off
	v_add_u32_e32 v145, v142, v133
	ds_write_b128 v145, v[32:35]
	v_lshl_add_u64 v[32:33], s[34:35], 0, v[116:117]
	global_load_dwordx4 v[32:35], v[32:33], off
	ds_write_b128 v136, v[36:39] offset:62464
	v_lshl_add_u64 v[36:37], s[0:1], 0, v[118:119]
	global_load_dwordx4 v[36:39], v[36:37], off
	v_add_u32_e32 v145, v141, v135
	ds_write_b128 v145, v[40:43]
	v_lshl_add_u64 v[40:41], s[28:29], 0, v[118:119]
	global_load_dwordx4 v[40:43], v[40:41], off
	v_add_u32_e32 v145, v142, v137
	ds_write_b128 v145, v[44:47]
	v_lshl_add_u64 v[44:45], s[34:35], 0, v[118:119]
	global_load_dwordx4 v[44:47], v[44:45], off
	ds_write_b128 v143, v[48:51]
	v_lshl_add_u64 v[48:49], s[60:61], 0, v[112:113]
	global_load_dwordx4 v[48:51], v[48:49], off
	ds_write_b128 v144, v[56:59]
	v_lshl_add_u64 v[56:57], s[60:61], 0, v[120:121]
	global_load_dwordx4 v[56:59], v[56:57], off
	s_waitcnt lgkmcnt(0)
	s_barrier
	s_waitcnt vmcnt(14)
	s_cmp_eq_u32 s100, 0
	s_cbranch_scc1 .Lpf_nopub_a0
	s_mov_b64 exec, 1
	v_mov_b32_e32 v239, s27
	v_or_b32_e32 v239, 1, v239
	global_store_dword v238, v239, s[98:99]
	s_mov_b64 exec, -1
.Lpf_nopub_a0:
	s_cmp_gt_u32 s27, 61
	s_cselect_b64 s[0:1], -1, 0
	s_and_b64 vcc, exec, s[0:1]
	s_cbranch_vccnz .LBB0_510
	s_min_u32 s7, s27, 59
	s_add_i32 s7, s7, 4
	s_mul_i32 s7, s3, s7
	s_add_u32 s7, s16, s7
	s_addc_u32 s40, s17, 0
	s_add_u32 s28, s7, s6
	s_addc_u32 s29, s40, 0
	s_add_u32 s34, s7, s14
	s_addc_u32 s35, s40, 0
	s_add_u32 s38, s7, s15
	s_addc_u32 s39, s40, 0
	s_add_u32 s60, s7, s26
	s_addc_u32 s61, s40, 0
	ds_write_b128 v124, v[52:55]
	v_lshl_add_u64 v[52:53], s[28:29], 0, v[112:113]
	global_load_dwordx4 v[52:55], v[52:53], off
	ds_write_b128 v124, v[60:63] offset:17408
	v_lshl_add_u64 v[60:61], s[34:35], 0, v[112:113]
	global_load_dwordx4 v[60:63], v[60:61], off
	ds_write_b128 v126, v[64:67] offset:34816
	v_lshl_add_u64 v[64:65], s[38:39], 0, v[112:113]
	global_load_dwordx4 v[64:67], v[64:65], off
	ds_write_b128 v128, v[68:71]
	v_lshl_add_u64 v[68:69], s[28:29], 0, v[114:115]
	global_load_dwordx4 v[68:71], v[68:69], off
	ds_write_b128 v128, v[72:75] offset:17408
	v_lshl_add_u64 v[72:73], s[34:35], 0, v[114:115]
	global_load_dwordx4 v[72:75], v[72:73], off
	ds_write_b128 v130, v[76:79] offset:34816
	v_lshl_add_u64 v[76:77], s[38:39], 0, v[114:115]
	global_load_dwordx4 v[76:79], v[76:77], off
	ds_write_b128 v132, v[80:83]
	v_lshl_add_u64 v[80:81], s[28:29], 0, v[116:117]
	global_load_dwordx4 v[80:83], v[80:81], off
	ds_write_b128 v132, v[84:87] offset:17408
	v_lshl_add_u64 v[84:85], s[34:35], 0, v[116:117]
	global_load_dwordx4 v[84:87], v[84:85], off
	ds_write_b128 v134, v[88:91] offset:34816
	v_lshl_add_u64 v[88:89], s[38:39], 0, v[116:117]
	global_load_dwordx4 v[88:91], v[88:89], off
	ds_write_b128 v136, v[92:95]
	v_lshl_add_u64 v[92:93], s[28:29], 0, v[118:119]
	global_load_dwordx4 v[92:95], v[92:93], off
	ds_write_b128 v136, v[96:99] offset:17408
	v_lshl_add_u64 v[96:97], s[34:35], 0, v[118:119]
	global_load_dwordx4 v[96:99], v[96:97], off
	ds_write_b128 v138, v[100:103] offset:34816
	v_lshl_add_u64 v[100:101], s[38:39], 0, v[118:119]
	global_load_dwordx4 v[100:103], v[100:101], off
	ds_write_b128 v139, v[104:107] offset:53248
	v_lshl_add_u64 v[104:105], s[60:61], 0, v[112:113]
	global_load_dwordx4 v[104:107], v[104:105], off
	ds_write_b128 v140, v[108:111] offset:53248
	v_lshl_add_u64 v[108:109], s[60:61], 0, v[120:121]
	global_load_dwordx4 v[108:111], v[108:109], off
	s_waitcnt lgkmcnt(0)
	s_barrier
	s_add_i32 s27, s27, 2
	s_branch .LBB0_511
